# v22 + attention K/V DMA in SGPR-base form + counted lgkmcnt waits in attention P.V
# speedup vs baseline: 1.0181x; 1.0020x over previous
; #define LAS __attribute__((address_space(3)))
; __device__ __forceinline__ void attn_issue_k(const Frame& F, const unsigned char* ktile, LAS unsigned char* buf) {
;     unsigned lo = F.lane * 16; asm volatile("" : "+v"(lo));
; #pragma unroll
;     for (int j = 0; j < 3; ++j) __builtin_amdgcn_global_load_lds((const unsigned*)(ktile + (size_t)(F.wave * 3 + j) * 1024 + lo), (LAS unsigned*)(buf + (F.wave * 3 + j) * 1024), 16, 0, 0);
; }
.LBB0_1006:
	s_min_u32 s89, s72, s45
	s_mul_i32 s0, s89, 0x6000
	s_add_u32 s92, s40, s0
	s_addc_u32 s93, s41, 0
	s_mul_i32 s0, s75, 0x6000
	v_mov_b32_e32 v2, v164
	s_add_i32 s0, s0, 0
	s_add_i32 m0, s0, s56
	s_add_u32 s98, s92, s8
	s_addc_u32 s99, s93, s9
	global_load_lds_dwordx4 v164, s[98:99]
	s_add_u32 s100, s92, s10
	s_addc_u32 s101, s93, s11
	s_add_i32 m0, s0, s57
	s_add_u32 s98, s92, s12
	s_addc_u32 s99, s93, s13
	global_load_lds_dwordx4 v164, s[100:101]
	s_add_i32 m0, s0, s58
	s_cmp_eq_u32 s74, 0
	global_load_lds_dwordx4 v164, s[98:99]
	s_mov_b32 s0, s91
	s_cbranch_scc1 .LBB0_1012
	s_sub_i32 s91, s74, 64
	s_cmp_gt_i32 s91, s70
	s_cbranch_scc1 .LBB0_1011
	s_cmp_le_i32 s74, s1
	s_cbranch_scc1 .LBB0_1010
	v_cmp_lt_i32_e32 vcc, -1, v184
	s_nop 1
	v_cndmask_b32_e32 v98, v167, v98, vcc
	v_cmp_lt_i32_e32 vcc, 31, v184
	s_nop 1
	v_cndmask_b32_e32 v82, v167, v82, vcc
	v_cmp_lt_i32_e32 vcc, 0, v184
	s_nop 1
	v_cndmask_b32_e32 v99, v167, v99, vcc
	v_cmp_lt_i32_e32 vcc, 32, v184
	s_nop 1
	v_cndmask_b32_e32 v83, v167, v83, vcc
	v_cmp_lt_i32_e32 vcc, 1, v184
	s_nop 1
	v_cndmask_b32_e32 v100, v167, v100, vcc
	v_cmp_lt_i32_e32 vcc, 33, v184
	s_nop 1
	v_cndmask_b32_e32 v84, v167, v84, vcc
	v_cmp_lt_i32_e32 vcc, 2, v184
	s_nop 1
	v_cndmask_b32_e32 v101, v167, v101, vcc
	v_cmp_lt_i32_e32 vcc, 34, v184
	s_nop 1
	v_cndmask_b32_e32 v85, v167, v85, vcc
	v_cmp_lt_i32_e32 vcc, 7, v184
	s_nop 1
	v_cndmask_b32_e32 v102, v167, v102, vcc
	v_cmp_lt_i32_e32 vcc, 39, v184
	s_nop 1
	v_cndmask_b32_e32 v86, v167, v86, vcc
	v_cmp_lt_i32_e32 vcc, 8, v184
	s_nop 1
	v_cndmask_b32_e32 v103, v167, v103, vcc
	v_cmp_lt_i32_e32 vcc, 40, v184
	s_nop 1
	v_cndmask_b32_e32 v87, v167, v87, vcc
	v_cmp_lt_i32_e32 vcc, 9, v184
	s_nop 1
	v_cndmask_b32_e32 v104, v167, v104, vcc
	v_cmp_lt_i32_e32 vcc, 41, v184
	s_nop 1
	v_cndmask_b32_e32 v88, v167, v88, vcc
	v_cmp_lt_i32_e32 vcc, 10, v184
	s_nop 1
	v_cndmask_b32_e32 v105, v167, v105, vcc
	v_cmp_lt_i32_e32 vcc, 42, v184
	s_nop 1
	v_cndmask_b32_e32 v89, v167, v89, vcc
	v_cmp_lt_i32_e32 vcc, 15, v184
	s_nop 1
	v_cndmask_b32_e32 v106, v167, v106, vcc
	v_cmp_lt_i32_e32 vcc, 47, v184
	s_nop 1
	v_cndmask_b32_e32 v90, v167, v90, vcc
	v_cmp_lt_i32_e32 vcc, 16, v184
	s_nop 1
	v_cndmask_b32_e32 v107, v167, v107, vcc
	v_cmp_lt_i32_e32 vcc, 48, v184
	s_nop 1
	v_cndmask_b32_e32 v91, v167, v91, vcc
	v_cmp_lt_i32_e32 vcc, 17, v184
	s_nop 1
	v_cndmask_b32_e32 v108, v167, v108, vcc
	v_cmp_lt_i32_e32 vcc, 49, v184
	s_nop 1
	v_cndmask_b32_e32 v92, v167, v92, vcc
	v_cmp_lt_i32_e32 vcc, 18, v184
	s_nop 1
	v_cndmask_b32_e32 v109, v167, v109, vcc
	v_cmp_lt_i32_e32 vcc, 50, v184
	s_nop 1
	v_cndmask_b32_e32 v93, v167, v93, vcc
	v_cmp_lt_i32_e32 vcc, 23, v184
	s_nop 1
	v_cndmask_b32_e32 v110, v167, v110, vcc
	v_cmp_lt_i32_e32 vcc, 55, v184
	s_nop 1
	v_cndmask_b32_e32 v94, v167, v94, vcc
	v_cmp_lt_i32_e32 vcc, 24, v184
	s_nop 1
	v_cndmask_b32_e32 v111, v167, v111, vcc
	v_cmp_lt_i32_e32 vcc, 56, v184
	s_nop 1
	v_cndmask_b32_e32 v95, v167, v95, vcc
	v_cmp_lt_i32_e32 vcc, 25, v184
	s_nop 1
	v_cndmask_b32_e32 v112, v167, v112, vcc
	v_cmp_lt_i32_e32 vcc, 57, v184
	s_nop 1
	v_cndmask_b32_e32 v96, v167, v96, vcc
	v_cmp_lt_i32_e32 vcc, 26, v184
	s_nop 1
	v_cndmask_b32_e32 v113, v167, v113, vcc
	v_cmp_lt_i32_e32 vcc, 58, v184
	s_nop 1
	v_cndmask_b32_e32 v97, v167, v97, vcc
.LBB0_1010:
	v_exp_f32_e32 v2, v98
	v_exp_f32_e32 v4, v99
	v_exp_f32_e32 v5, v100
	v_exp_f32_e32 v6, v101
	v_add_f32_e32 v7, 0, v2
	v_exp_f32_e32 v8, v102
	v_add_f32_e32 v7, v4, v7
	v_exp_f32_e32 v9, v103
	v_add_f32_e32 v7, v5, v7
	v_exp_f32_e32 v10, v104
	v_add_f32_e32 v7, v6, v7
	v_exp_f32_e32 v11, v105
	v_add_f32_e32 v7, v8, v7
	v_exp_f32_e32 v16, v106
	v_add_f32_e32 v7, v9, v7
	v_exp_f32_e32 v106, v107
	v_add_f32_e32 v7, v10, v7
	v_exp_f32_e32 v107, v108
	v_add_f32_e32 v7, v11, v7
	v_exp_f32_e32 v108, v109
	v_add_f32_e32 v7, v16, v7
	v_exp_f32_e32 v109, v110
	v_add_f32_e32 v7, v106, v7
	v_exp_f32_e32 v110, v111
	v_add_f32_e32 v7, v107, v7
	v_exp_f32_e32 v111, v112
	v_add_f32_e32 v7, v108, v7
	v_exp_f32_e32 v112, v113
	v_add_f32_e32 v7, v109, v7
	s_lshl_b32 s90, s90, 14
	v_add_f32_e32 v7, v110, v7
	s_add_i32 s90, s90, 0x12000
	v_add_f32_e32 v7, v111, v7
	v_cvt_pk_bf16_f32 v4, v2, v4
	v_add_u32_e32 v2, s90, v163
	v_add_f32_e32 v17, v112, v7
	v_cvt_pk_bf16_f32 v5, v5, v6
	v_cvt_pk_bf16_f32 v6, v8, v9
	v_cvt_pk_bf16_f32 v7, v10, v11
	ds_read_b128 v[8:11], v2
	ds_read_b128 v[12:15], v2 offset:4096
	ds_read_b128 v[98:101], v2 offset:8192
	ds_read_b128 v[102:105], v2 offset:12288
	v_cvt_pk_bf16_f32 v106, v16, v106
	v_cvt_pk_bf16_f32 v107, v107, v108
	v_cvt_pk_bf16_f32 v108, v109, v110
	v_cvt_pk_bf16_f32 v109, v111, v112
	v_add_u32_e32 v2, s90, v171
	ds_read_b128 v[110:113], v2
	ds_read_b128 v[186:189], v2 offset:4096
	ds_read_b128 v[190:193], v2 offset:8192
	ds_read_b128 v[194:197], v2 offset:12288
	s_waitcnt lgkmcnt(7)
	v_mfma_f32_32x32x16_bf16 v[66:81], v[8:11], v[4:7], v[66:81]
	v_exp_f32_e32 v2, v82
	v_exp_f32_e32 v185, v83
	s_nop 0
	v_add_f32_e32 v199, v2, v185
	s_waitcnt lgkmcnt(6)
	v_mfma_f32_32x32x16_bf16 v[50:65], v[12:15], v[4:7], v[50:65]
	v_exp_f32_e32 v198, v84
	v_exp_f32_e32 v16, v85
	s_nop 0
	v_pk_add_f32 v[8:9], v[198:199], v[16:17]
	s_nop 0
	v_pk_add_f32 v[200:201], v[8:9], v[8:9] op_sel_hi:[0,1]
	s_waitcnt lgkmcnt(5)
	v_mfma_f32_32x32x16_bf16 v[34:49], v[98:101], v[4:7], v[34:49]
	v_exp_f32_e32 v17, v86
	v_exp_f32_e32 v199, v87
	s_nop 0
	v_add_f32_e32 v203, v17, v199
	s_waitcnt lgkmcnt(4)
	v_mfma_f32_32x32x16_bf16 v[18:33], v[102:105], v[4:7], v[18:33]
	v_exp_f32_e32 v202, v88
	v_exp_f32_e32 v200, v89
	s_nop 0
	v_pk_add_f32 v[8:9], v[202:203], v[200:201]
	s_nop 0
	v_pk_add_f32 v[204:205], v[8:9], v[8:9] op_sel_hi:[0,1]
	v_add_u32_e32 v82, s90, v172
	ds_read_b128 v[4:7], v82
	ds_read_b128 v[8:11], v82 offset:4096
	ds_read_b128 v[12:15], v82 offset:8192
	ds_read_b128 v[82:85], v82 offset:12288
	s_waitcnt lgkmcnt(7)
	v_mfma_f32_32x32x16_bf16 v[66:81], v[110:113], v[106:109], v[66:81]
	v_exp_f32_e32 v201, v90
	v_exp_f32_e32 v203, v91
	s_nop 0
	v_add_f32_e32 v207, v201, v203
	s_waitcnt lgkmcnt(6)
	v_mfma_f32_32x32x16_bf16 v[50:65], v[186:189], v[106:109], v[50:65]
	v_exp_f32_e32 v206, v92
	v_exp_f32_e32 v204, v93
	s_nop 0
	v_pk_add_f32 v[86:87], v[206:207], v[204:205]
	s_nop 0
	v_pk_add_f32 v[110:111], v[86:87], v[86:87] op_sel_hi:[0,1]
	s_waitcnt lgkmcnt(5)
	v_mfma_f32_32x32x16_bf16 v[34:49], v[190:193], v[106:109], v[34:49]
	v_exp_f32_e32 v186, v94
	v_exp_f32_e32 v187, v95
	s_nop 0
	v_add_f32_e32 v113, v186, v187
	s_waitcnt lgkmcnt(4)
	v_mfma_f32_32x32x16_bf16 v[18:33], v[194:197], v[106:109], v[18:33]
	v_exp_f32_e32 v112, v96
	v_exp_f32_e32 v110, v97
	s_nop 0
	v_pk_add_f32 v[86:87], v[112:113], v[110:111]
	s_nop 0
	v_add_f32_e32 v102, v86, v87
	v_add_u32_e32 v98, s90, v173
	ds_read_b128 v[86:89], v98
	ds_read_b128 v[90:93], v98 offset:4096
	ds_read_b128 v[94:97], v98 offset:8192
	ds_read_b128 v[98:101], v98 offset:12288
	v_add_f32_e32 v178, v178, v102
	v_cvt_pk_bf16_f32 v102, v2, v185
	v_cvt_pk_bf16_f32 v103, v198, v16
	v_cvt_pk_bf16_f32 v104, v17, v199
	v_cvt_pk_bf16_f32 v105, v202, v200
	v_cvt_pk_bf16_f32 v106, v201, v203
	v_cvt_pk_bf16_f32 v107, v206, v204
	v_cvt_pk_bf16_f32 v108, v186, v187
	v_cvt_pk_bf16_f32 v109, v112, v110
	s_waitcnt lgkmcnt(7)
	v_mfma_f32_32x32x16_bf16 v[66:81], v[4:7], v[102:105], v[66:81]
	s_waitcnt lgkmcnt(6)
	v_mfma_f32_32x32x16_bf16 v[50:65], v[8:11], v[102:105], v[50:65]
	s_waitcnt lgkmcnt(5)
	v_mfma_f32_32x32x16_bf16 v[34:49], v[12:15], v[102:105], v[34:49]
	s_waitcnt lgkmcnt(4)
	v_mfma_f32_32x32x16_bf16 v[18:33], v[82:85], v[102:105], v[18:33]
	s_waitcnt lgkmcnt(0)
	v_mfma_f32_32x32x16_bf16 v[66:81], v[86:89], v[106:109], v[66:81]
	v_mfma_f32_32x32x16_bf16 v[50:65], v[90:93], v[106:109], v[50:65]
	v_mfma_f32_32x32x16_bf16 v[34:49], v[94:97], v[106:109], v[34:49]
	v_mfma_f32_32x32x16_bf16 v[18:33], v[98:101], v[106:109], v[18:33]

; #define LAS __attribute__((address_space(3)))
; __device__ __forceinline__ void attn_issue_v(const Frame& F, const unsigned char* vtile, LAS unsigned char* buf) {
;     unsigned lo = F.lane * 16; asm volatile("" : "+v"(lo));
; #pragma unroll
;     for (int j = 0; j < 2; ++j) __builtin_amdgcn_global_load_lds((const unsigned*)(vtile + (size_t)(F.wave * 2 + j) * 1024 + lo), (LAS unsigned*)(buf + (F.wave * 2 + j) * 1024), 16, 0, 0);
; }
.LBB0_1013:
	s_lshl_b32 s89, s89, 14
	s_add_u32 s92, s42, s89
	s_addc_u32 s93, s43, 0
	s_lshl_b32 s89, s75, 14
	s_waitcnt vmcnt(8)
	s_add_i32 s89, s89, 0
	v_mov_b32_e32 v2, v164
	s_waitcnt lgkmcnt(0)
	s_barrier
	s_add_i32 s89, s89, 0x12000
	s_add_i32 m0, s89, s59
	s_add_u32 s98, s92, s14
	s_addc_u32 s99, s93, s15
	global_load_lds_dwordx4 v164, s[98:99]
	s_add_u32 s100, s92, s16
	s_addc_u32 s101, s93, s17
	s_add_i32 m0, s89, s60
	s_cmp_gt_i32 s90, s70
	global_load_lds_dwordx4 v164, s[100:101]
	s_cbranch_scc1 .LBB0_1015
	s_mul_i32 s89, s0, 0x6000
	v_add_u32_e32 v2, s89, v174
	v_add_u32_e32 v16, s89, v175
	ds_read_b128 v[4:7], v2
	ds_read_b128 v[8:11], v2 offset:12288
	ds_read_b128 v[12:15], v16
	ds_read_b128 v[186:189], v16 offset:12288
	v_add_u32_e32 v17, s89, v176
	v_add_u32_e32 v185, s89, v177
	ds_read_b128 v[190:193], v17
	ds_read_b128 v[194:197], v17 offset:12288
	ds_read_b128 v[198:201], v185
	ds_read_b128 v[202:205], v185 offset:12288
	ds_read_b128 v[206:209], v2 offset:128
	ds_read_b128 v[210:213], v2 offset:12416
	ds_read_b128 v[214:217], v16 offset:128
	ds_read_b128 v[218:221], v16 offset:12416
	s_waitcnt lgkmcnt(8)
	v_mfma_f32_32x32x16_bf16 v[98:113], v[4:7], v[114:117], 0
	v_mfma_f32_32x32x16_bf16 v[98:113], v[12:15], v[118:121], v[98:113]
	v_mfma_f32_32x32x16_bf16 v[82:97], v[8:11], v[114:117], 0
	v_mfma_f32_32x32x16_bf16 v[82:97], v[186:189], v[118:121], v[82:97]
	ds_read_b128 v[4:7], v17 offset:128
	ds_read_b128 v[8:11], v17 offset:12416
	ds_read_b128 v[12:15], v185 offset:128
	ds_read_b128 v[186:189], v185 offset:12416
	s_waitcnt lgkmcnt(8)
	v_mfma_f32_32x32x16_bf16 v[98:113], v[190:193], v[122:125], v[98:113]
	v_mfma_f32_32x32x16_bf16 v[98:113], v[198:201], v[126:129], v[98:113]
	v_mfma_f32_32x32x16_bf16 v[82:97], v[194:197], v[122:125], v[82:97]
	v_mfma_f32_32x32x16_bf16 v[82:97], v[202:205], v[126:129], v[82:97]
	ds_read_b128 v[190:193], v2 offset:256
	ds_read_b128 v[194:197], v2 offset:12544
	ds_read_b128 v[198:201], v16 offset:256
	ds_read_b128 v[202:205], v16 offset:12544
	s_waitcnt lgkmcnt(8)
	v_mfma_f32_32x32x16_bf16 v[98:113], v[206:209], v[130:133], v[98:113]
	v_mfma_f32_32x32x16_bf16 v[98:113], v[214:217], v[134:137], v[98:113]
	v_mfma_f32_32x32x16_bf16 v[82:97], v[210:213], v[130:133], v[82:97]
	v_mfma_f32_32x32x16_bf16 v[82:97], v[218:221], v[134:137], v[82:97]
	ds_read_b128 v[206:209], v17 offset:256
	ds_read_b128 v[210:213], v17 offset:12544
	ds_read_b128 v[214:217], v185 offset:256
	ds_read_b128 v[218:221], v185 offset:12544
	s_waitcnt lgkmcnt(8)
	v_mfma_f32_32x32x16_bf16 v[98:113], v[4:7], v[138:141], v[98:113]
	v_mfma_f32_32x32x16_bf16 v[98:113], v[12:15], v[142:145], v[98:113]
	v_mfma_f32_32x32x16_bf16 v[82:97], v[8:11], v[138:141], v[82:97]
	v_mfma_f32_32x32x16_bf16 v[82:97], v[186:189], v[142:145], v[82:97]
	s_waitcnt lgkmcnt(4)
	v_mfma_f32_32x32x16_bf16 v[98:113], v[190:193], v[146:149], v[98:113]
	v_mfma_f32_32x32x16_bf16 v[98:113], v[198:201], v[154:157], v[98:113]
	v_mfma_f32_32x32x16_bf16 v[82:97], v[194:197], v[146:149], v[82:97]
	v_mfma_f32_32x32x16_bf16 v[82:97], v[202:205], v[154:157], v[82:97]
	s_waitcnt lgkmcnt(0)
	v_mfma_f32_32x32x16_bf16 v[98:113], v[206:209], v[150:153], v[98:113]
	v_mfma_f32_32x32x16_bf16 v[98:113], v[214:217], v[158:161], v[98:113]
	v_mfma_f32_32x32x16_bf16 v[82:97], v[210:213], v[150:153], v[82:97]
	v_mfma_f32_32x32x16_bf16 v[82:97], v[218:221], v[158:161], v[82:97]
	s_branch .LBB0_1016

.LBB0_1021:
	v_exp_f32_e32 v2, v98
	v_exp_f32_e32 v4, v99
	v_exp_f32_e32 v5, v100
	v_exp_f32_e32 v6, v101
	v_add_f32_e32 v7, 0, v2
	v_exp_f32_e32 v8, v102
	v_add_f32_e32 v7, v4, v7
	v_exp_f32_e32 v9, v103
	v_add_f32_e32 v7, v5, v7
	v_exp_f32_e32 v10, v104
	v_add_f32_e32 v7, v6, v7
	v_exp_f32_e32 v11, v105
	v_add_f32_e32 v7, v8, v7
	v_exp_f32_e32 v16, v106
	v_add_f32_e32 v7, v9, v7
	v_exp_f32_e32 v106, v107
	v_add_f32_e32 v7, v10, v7
	v_exp_f32_e32 v107, v108
	v_add_f32_e32 v7, v11, v7
	v_exp_f32_e32 v108, v109
	v_add_f32_e32 v7, v16, v7
	v_exp_f32_e32 v109, v110
	v_add_f32_e32 v7, v106, v7
	v_exp_f32_e32 v110, v111
	v_add_f32_e32 v7, v107, v7
	v_exp_f32_e32 v111, v112
	v_add_f32_e32 v7, v108, v7
	v_exp_f32_e32 v112, v113
	s_lshl_b32 s0, s0, 14
	v_add_f32_e32 v7, v109, v7
	s_add_i32 s0, s0, 0
	v_add_f32_e32 v7, v110, v7
	s_add_i32 s0, s0, 0x12000
	v_add_f32_e32 v7, v111, v7
	v_cvt_pk_bf16_f32 v4, v2, v4
	v_add_u32_e32 v2, s0, v183
	v_add_f32_e32 v17, v112, v7
	v_cvt_pk_bf16_f32 v5, v5, v6
	v_cvt_pk_bf16_f32 v6, v8, v9
	v_cvt_pk_bf16_f32 v7, v10, v11
	ds_read_b128 v[8:11], v2
	ds_read_b128 v[12:15], v2 offset:4096
	ds_read_b128 v[98:101], v2 offset:8192
	ds_read_b128 v[102:105], v2 offset:12288
	v_cvt_pk_bf16_f32 v106, v16, v106
	v_cvt_pk_bf16_f32 v107, v107, v108
	v_cvt_pk_bf16_f32 v108, v109, v110
	v_cvt_pk_bf16_f32 v109, v111, v112
	v_add_u32_e32 v2, s0, v182
	ds_read_b128 v[110:113], v2
	ds_read_b128 v[182:185], v2 offset:4096
	ds_read_b128 v[186:189], v2 offset:8192
	ds_read_b128 v[190:193], v2 offset:12288
	s_waitcnt lgkmcnt(7)
	v_mfma_f32_32x32x16_bf16 v[66:81], v[8:11], v[4:7], v[66:81]
	v_exp_f32_e32 v2, v82
	v_exp_f32_e32 v170, v83
	s_nop 0
	v_add_f32_e32 v195, v2, v170
	s_waitcnt lgkmcnt(6)
	v_mfma_f32_32x32x16_bf16 v[50:65], v[12:15], v[4:7], v[50:65]
	v_exp_f32_e32 v194, v84
	v_exp_f32_e32 v16, v85
	s_nop 0
	v_pk_add_f32 v[8:9], v[194:195], v[16:17]
	s_nop 0
	v_pk_add_f32 v[196:197], v[8:9], v[8:9] op_sel_hi:[0,1]
	s_waitcnt lgkmcnt(5)
	v_mfma_f32_32x32x16_bf16 v[34:49], v[98:101], v[4:7], v[34:49]
	v_exp_f32_e32 v17, v86
	v_exp_f32_e32 v195, v87
	s_nop 0
	v_add_f32_e32 v199, v17, v195
	s_waitcnt lgkmcnt(4)
	v_mfma_f32_32x32x16_bf16 v[18:33], v[102:105], v[4:7], v[18:33]
	v_exp_f32_e32 v198, v88
	v_exp_f32_e32 v196, v89
	s_nop 0
	v_pk_add_f32 v[8:9], v[198:199], v[196:197]
	s_nop 0
	v_pk_add_f32 v[200:201], v[8:9], v[8:9] op_sel_hi:[0,1]
	v_add_u32_e32 v82, s0, v181
	ds_read_b128 v[4:7], v82
	ds_read_b128 v[8:11], v82 offset:4096
	ds_read_b128 v[12:15], v82 offset:8192
	ds_read_b128 v[82:85], v82 offset:12288
	s_waitcnt lgkmcnt(7)
	v_mfma_f32_32x32x16_bf16 v[66:81], v[110:113], v[106:109], v[66:81]
	v_exp_f32_e32 v181, v90
	v_exp_f32_e32 v197, v91
	s_nop 0
	v_add_f32_e32 v203, v181, v197
	s_waitcnt lgkmcnt(6)
	v_mfma_f32_32x32x16_bf16 v[50:65], v[182:185], v[106:109], v[50:65]
	v_exp_f32_e32 v202, v92
	v_exp_f32_e32 v200, v93
	s_nop 0
	v_pk_add_f32 v[86:87], v[202:203], v[200:201]
	s_nop 0
	v_pk_add_f32 v[110:111], v[86:87], v[86:87] op_sel_hi:[0,1]
	s_waitcnt lgkmcnt(5)
	v_mfma_f32_32x32x16_bf16 v[34:49], v[186:189], v[106:109], v[34:49]
	v_exp_f32_e32 v182, v94
	v_exp_f32_e32 v183, v95
	s_nop 0
	v_add_f32_e32 v113, v182, v183
	s_waitcnt lgkmcnt(4)
	v_mfma_f32_32x32x16_bf16 v[18:33], v[190:193], v[106:109], v[18:33]
	v_exp_f32_e32 v112, v96
	v_exp_f32_e32 v110, v97
	s_nop 0
	v_pk_add_f32 v[86:87], v[112:113], v[110:111]
	s_nop 0
	v_add_f32_e32 v102, v86, v87
	v_add_u32_e32 v98, s0, v180
	ds_read_b128 v[86:89], v98
	ds_read_b128 v[90:93], v98 offset:4096
	ds_read_b128 v[94:97], v98 offset:8192
	ds_read_b128 v[98:101], v98 offset:12288
	v_add_f32_e32 v178, v178, v102
	v_cvt_pk_bf16_f32 v102, v2, v170
	v_cvt_pk_bf16_f32 v103, v194, v16
	v_cvt_pk_bf16_f32 v104, v17, v195
	v_cvt_pk_bf16_f32 v105, v198, v196
	v_cvt_pk_bf16_f32 v106, v181, v197
	v_cvt_pk_bf16_f32 v107, v202, v200
	v_cvt_pk_bf16_f32 v108, v182, v183
	v_cvt_pk_bf16_f32 v109, v112, v110
	s_waitcnt lgkmcnt(7)
	v_mfma_f32_32x32x16_bf16 v[66:81], v[4:7], v[102:105], v[66:81]
	s_waitcnt lgkmcnt(6)
	v_mfma_f32_32x32x16_bf16 v[50:65], v[8:11], v[102:105], v[50:65]
	s_waitcnt lgkmcnt(5)
	v_mfma_f32_32x32x16_bf16 v[34:49], v[12:15], v[102:105], v[34:49]
	s_waitcnt lgkmcnt(4)
	v_mfma_f32_32x32x16_bf16 v[18:33], v[82:85], v[102:105], v[18:33]
	s_waitcnt lgkmcnt(0)
	v_mfma_f32_32x32x16_bf16 v[66:81], v[86:89], v[106:109], v[66:81]
	v_mfma_f32_32x32x16_bf16 v[50:65], v[90:93], v[106:109], v[50:65]
	v_mfma_f32_32x32x16_bf16 v[34:49], v[94:97], v[106:109], v[34:49]
	v_mfma_f32_32x32x16_bf16 v[18:33], v[98:101], v[106:109], v[18:33]

.LBB0_1025:
	v_exp_f32_e32 v2, v98
	v_exp_f32_e32 v4, v99
	v_exp_f32_e32 v5, v100
	v_exp_f32_e32 v6, v101
	v_add_f32_e32 v7, 0, v2
	v_exp_f32_e32 v8, v102
	v_add_f32_e32 v7, v4, v7
	v_exp_f32_e32 v9, v103
	v_add_f32_e32 v7, v5, v7
	v_exp_f32_e32 v10, v104
	v_add_f32_e32 v7, v6, v7
	v_exp_f32_e32 v11, v105
	v_add_f32_e32 v7, v8, v7
	v_exp_f32_e32 v16, v106
	v_add_f32_e32 v7, v9, v7
	v_exp_f32_e32 v106, v107
	v_add_f32_e32 v7, v10, v7
	v_exp_f32_e32 v107, v108
	v_add_f32_e32 v7, v11, v7
	v_exp_f32_e32 v108, v109
	v_add_f32_e32 v7, v16, v7
	v_exp_f32_e32 v109, v110
	v_add_f32_e32 v7, v106, v7
	v_exp_f32_e32 v110, v111
	v_add_f32_e32 v7, v107, v7
	v_exp_f32_e32 v111, v112
	v_add_f32_e32 v7, v108, v7
	v_exp_f32_e32 v112, v113
	v_add_f32_e32 v7, v109, v7
	s_lshl_b32 s0, s73, 14
	v_add_f32_e32 v7, v110, v7
	s_add_i32 s0, s0, 0x12000
	v_add_f32_e32 v7, v111, v7
	v_cvt_pk_bf16_f32 v4, v2, v4
	v_add_u32_e32 v2, s0, v163
	v_add_f32_e32 v17, v112, v7
	v_cvt_pk_bf16_f32 v5, v5, v6
	v_cvt_pk_bf16_f32 v6, v8, v9
	v_cvt_pk_bf16_f32 v7, v10, v11
	ds_read_b128 v[8:11], v2
	ds_read_b128 v[12:15], v2 offset:4096
	ds_read_b128 v[98:101], v2 offset:8192
	ds_read_b128 v[102:105], v2 offset:12288
	v_cvt_pk_bf16_f32 v106, v16, v106
	v_cvt_pk_bf16_f32 v107, v107, v108
	v_cvt_pk_bf16_f32 v108, v109, v110
	v_cvt_pk_bf16_f32 v109, v111, v112
	v_add_u32_e32 v2, s0, v171
	ds_read_b128 v[110:113], v2
	ds_read_b128 v[180:183], v2 offset:4096
	ds_read_b128 v[184:187], v2 offset:8192
	ds_read_b128 v[188:191], v2 offset:12288
	s_waitcnt lgkmcnt(7)
	v_mfma_f32_32x32x16_bf16 v[66:81], v[8:11], v[4:7], v[66:81]
	v_exp_f32_e32 v2, v82
	v_exp_f32_e32 v179, v83
	s_nop 0
	v_add_f32_e32 v193, v2, v179
	s_waitcnt lgkmcnt(6)
	v_mfma_f32_32x32x16_bf16 v[50:65], v[12:15], v[4:7], v[50:65]
	v_exp_f32_e32 v192, v84
	v_exp_f32_e32 v16, v85
	s_nop 0
	v_pk_add_f32 v[8:9], v[192:193], v[16:17]
	s_nop 0
	v_pk_add_f32 v[194:195], v[8:9], v[8:9] op_sel_hi:[0,1]
	s_waitcnt lgkmcnt(5)
	v_mfma_f32_32x32x16_bf16 v[34:49], v[98:101], v[4:7], v[34:49]
	v_exp_f32_e32 v17, v86
	v_exp_f32_e32 v193, v87
	s_nop 0
	v_add_f32_e32 v197, v17, v193
	s_waitcnt lgkmcnt(4)
	v_mfma_f32_32x32x16_bf16 v[18:33], v[102:105], v[4:7], v[18:33]
	v_exp_f32_e32 v196, v88
	v_exp_f32_e32 v194, v89
	s_nop 0
	v_pk_add_f32 v[8:9], v[196:197], v[194:195]
	s_nop 0
	v_pk_add_f32 v[198:199], v[8:9], v[8:9] op_sel_hi:[0,1]
	v_add_u32_e32 v82, s0, v172
	ds_read_b128 v[4:7], v82
	ds_read_b128 v[8:11], v82 offset:4096
	ds_read_b128 v[12:15], v82 offset:8192
	ds_read_b128 v[82:85], v82 offset:12288
	s_waitcnt lgkmcnt(7)
	v_mfma_f32_32x32x16_bf16 v[66:81], v[110:113], v[106:109], v[66:81]
	v_exp_f32_e32 v195, v90
	v_exp_f32_e32 v197, v91
	s_nop 0
	v_add_f32_e32 v201, v195, v197
	s_waitcnt lgkmcnt(6)
	v_mfma_f32_32x32x16_bf16 v[50:65], v[180:183], v[106:109], v[50:65]
	v_exp_f32_e32 v200, v92
	v_exp_f32_e32 v198, v93
	s_nop 0
	v_pk_add_f32 v[86:87], v[200:201], v[198:199]
	s_nop 0
	v_pk_add_f32 v[110:111], v[86:87], v[86:87] op_sel_hi:[0,1]
	s_waitcnt lgkmcnt(5)
	v_mfma_f32_32x32x16_bf16 v[34:49], v[184:187], v[106:109], v[34:49]
	v_exp_f32_e32 v180, v94
	v_exp_f32_e32 v181, v95
	s_nop 0
	v_add_f32_e32 v113, v180, v181
	s_waitcnt lgkmcnt(4)
	v_mfma_f32_32x32x16_bf16 v[18:33], v[188:191], v[106:109], v[18:33]
	v_exp_f32_e32 v112, v96
	v_exp_f32_e32 v110, v97
	s_nop 0
	v_pk_add_f32 v[86:87], v[112:113], v[110:111]
	s_nop 0
	v_add_f32_e32 v102, v86, v87
	v_add_u32_e32 v98, s0, v173
	ds_read_b128 v[86:89], v98
	ds_read_b128 v[90:93], v98 offset:4096
	ds_read_b128 v[94:97], v98 offset:8192
	ds_read_b128 v[98:101], v98 offset:12288
	v_add_f32_e32 v178, v178, v102
	v_cvt_pk_bf16_f32 v102, v2, v179
	v_cvt_pk_bf16_f32 v103, v192, v16
	v_cvt_pk_bf16_f32 v104, v17, v193
	v_cvt_pk_bf16_f32 v105, v196, v194
	v_cvt_pk_bf16_f32 v106, v195, v197
	v_cvt_pk_bf16_f32 v107, v200, v198
	v_cvt_pk_bf16_f32 v108, v180, v181
	v_cvt_pk_bf16_f32 v109, v112, v110
	s_waitcnt lgkmcnt(7)
	v_mfma_f32_32x32x16_bf16 v[66:81], v[4:7], v[102:105], v[66:81]
	s_waitcnt lgkmcnt(6)
	v_mfma_f32_32x32x16_bf16 v[50:65], v[8:11], v[102:105], v[50:65]
	s_waitcnt lgkmcnt(5)
	v_mfma_f32_32x32x16_bf16 v[34:49], v[12:15], v[102:105], v[34:49]
	s_waitcnt lgkmcnt(4)
	v_mfma_f32_32x32x16_bf16 v[18:33], v[82:85], v[102:105], v[18:33]
	s_waitcnt lgkmcnt(0)
	v_mfma_f32_32x32x16_bf16 v[66:81], v[86:89], v[106:109], v[66:81]
	v_mfma_f32_32x32x16_bf16 v[50:65], v[90:93], v[106:109], v[50:65]
	v_mfma_f32_32x32x16_bf16 v[34:49], v[94:97], v[106:109], v[34:49]
	v_mfma_f32_32x32x16_bf16 v[18:33], v[98:101], v[106:109], v[18:33]

; #define LAS __attribute__((address_space(3)))
; __device__ __forceinline__ void attn_issue_k(const Frame& F, const unsigned char* ktile, LAS unsigned char* buf) {
;     unsigned lo = F.lane * 16; asm volatile("" : "+v"(lo));
; #pragma unroll
;     for (int j = 0; j < 3; ++j) __builtin_amdgcn_global_load_lds((const unsigned*)(ktile + (size_t)(F.wave * 3 + j) * 1024 + lo), (LAS unsigned*)(buf + (F.wave * 3 + j) * 1024), 16, 0, 0);
; }
.LBB0_1027:
	s_min_u32 s75, s33, s45
	s_mul_i32 s0, s75, 0x6000
	s_add_u32 s0, s40, s0
	s_addc_u32 s1, s41, 0
	s_mul_i32 s88, s74, 0x6000
	v_mov_b32_e32 v2, v164
	s_add_i32 s88, s88, 0
	s_add_i32 m0, s88, s56
	s_add_u32 s98, s0, s8
	s_addc_u32 s99, s1, s9
	global_load_lds_dwordx4 v164, s[98:99]
	s_add_u32 s100, s0, s10
	s_addc_u32 s101, s1, s11
	s_add_i32 m0, s88, s57
	s_add_u32 s98, s0, s12
	s_addc_u32 s99, s1, s13
	global_load_lds_dwordx4 v164, s[100:101]
	s_add_i32 m0, s88, s58
	s_cmp_le_u32 s72, s70
	global_load_lds_dwordx4 v164, s[98:99]
	s_cselect_b64 s[0:1], -1, 0
	s_cmp_gt_u32 s72, s70
	s_cbranch_scc1 .LBB0_1029
	s_mul_i32 s88, s73, 0x6000
	v_add_u32_e32 v2, s88, v174
	v_add_u32_e32 v16, s88, v175
	ds_read_b128 v[4:7], v2
	ds_read_b128 v[8:11], v2 offset:12288
	ds_read_b128 v[12:15], v16
	ds_read_b128 v[180:183], v16 offset:12288
	v_add_u32_e32 v17, s88, v176
	v_add_u32_e32 v179, s88, v177
	ds_read_b128 v[184:187], v17
	ds_read_b128 v[188:191], v17 offset:12288
	ds_read_b128 v[192:195], v179
	ds_read_b128 v[196:199], v179 offset:12288
	ds_read_b128 v[200:203], v2 offset:128
	ds_read_b128 v[204:207], v2 offset:12416
	ds_read_b128 v[208:211], v16 offset:128
	ds_read_b128 v[212:215], v16 offset:12416
	s_waitcnt lgkmcnt(8)
	v_mfma_f32_32x32x16_bf16 v[98:113], v[4:7], v[114:117], 0
	v_mfma_f32_32x32x16_bf16 v[98:113], v[12:15], v[118:121], v[98:113]
	v_mfma_f32_32x32x16_bf16 v[82:97], v[8:11], v[114:117], 0
	v_mfma_f32_32x32x16_bf16 v[82:97], v[180:183], v[118:121], v[82:97]
	ds_read_b128 v[4:7], v17 offset:128
	ds_read_b128 v[8:11], v17 offset:12416
	ds_read_b128 v[12:15], v179 offset:128
	ds_read_b128 v[180:183], v179 offset:12416
	s_waitcnt lgkmcnt(8)
	v_mfma_f32_32x32x16_bf16 v[98:113], v[184:187], v[122:125], v[98:113]
	v_mfma_f32_32x32x16_bf16 v[98:113], v[192:195], v[126:129], v[98:113]
	v_mfma_f32_32x32x16_bf16 v[82:97], v[188:191], v[122:125], v[82:97]
	v_mfma_f32_32x32x16_bf16 v[82:97], v[196:199], v[126:129], v[82:97]
	ds_read_b128 v[184:187], v2 offset:256
	ds_read_b128 v[188:191], v2 offset:12544
	ds_read_b128 v[192:195], v16 offset:256
	ds_read_b128 v[196:199], v16 offset:12544
	s_waitcnt lgkmcnt(8)
	v_mfma_f32_32x32x16_bf16 v[98:113], v[200:203], v[130:133], v[98:113]
	v_mfma_f32_32x32x16_bf16 v[98:113], v[208:211], v[134:137], v[98:113]
	v_mfma_f32_32x32x16_bf16 v[82:97], v[204:207], v[130:133], v[82:97]
	v_mfma_f32_32x32x16_bf16 v[82:97], v[212:215], v[134:137], v[82:97]
	ds_read_b128 v[200:203], v17 offset:256
	ds_read_b128 v[204:207], v17 offset:12544
	ds_read_b128 v[208:211], v179 offset:256
	ds_read_b128 v[212:215], v179 offset:12544
	s_waitcnt lgkmcnt(8)
	v_mfma_f32_32x32x16_bf16 v[98:113], v[4:7], v[138:141], v[98:113]
	v_mfma_f32_32x32x16_bf16 v[98:113], v[12:15], v[142:145], v[98:113]
	v_mfma_f32_32x32x16_bf16 v[82:97], v[8:11], v[138:141], v[82:97]
	v_mfma_f32_32x32x16_bf16 v[82:97], v[180:183], v[142:145], v[82:97]
	s_waitcnt lgkmcnt(4)
	v_mfma_f32_32x32x16_bf16 v[98:113], v[184:187], v[146:149], v[98:113]
	v_mfma_f32_32x32x16_bf16 v[98:113], v[192:195], v[154:157], v[98:113]
	v_mfma_f32_32x32x16_bf16 v[82:97], v[188:191], v[146:149], v[82:97]
	v_mfma_f32_32x32x16_bf16 v[82:97], v[196:199], v[154:157], v[82:97]
	s_waitcnt lgkmcnt(0)
	v_mfma_f32_32x32x16_bf16 v[98:113], v[200:203], v[150:153], v[98:113]
	v_mfma_f32_32x32x16_bf16 v[98:113], v[208:211], v[158:161], v[98:113]
	v_mfma_f32_32x32x16_bf16 v[82:97], v[204:207], v[150:153], v[82:97]
	v_mfma_f32_32x32x16_bf16 v[82:97], v[212:215], v[158:161], v[82:97]
	s_branch .LBB0_1030

; #define LAS __attribute__((address_space(3)))
; __device__ __forceinline__ void attn_issue_v(const Frame& F, const unsigned char* vtile, LAS unsigned char* buf) {
;     unsigned lo = F.lane * 16; asm volatile("" : "+v"(lo));
; #pragma unroll
;     for (int j = 0; j < 2; ++j) __builtin_amdgcn_global_load_lds((const unsigned*)(vtile + (size_t)(F.wave * 2 + j) * 1024 + lo), (LAS unsigned*)(buf + (F.wave * 2 + j) * 1024), 16, 0, 0);
; }
.LBB0_1030:
	s_lshl_b32 s75, s75, 14
	s_add_u32 s88, s42, s75
	s_addc_u32 s89, s43, 0
	s_lshl_b32 s75, s74, 14
	s_waitcnt vmcnt(8)
	s_add_i32 s75, s75, 0
	v_mov_b32_e32 v2, v164
	s_waitcnt lgkmcnt(0)
	s_barrier
	s_add_i32 s75, s75, 0x12000
	s_add_i32 m0, s75, s59
	s_add_u32 s98, s88, s14
	s_addc_u32 s99, s89, s15
	global_load_lds_dwordx4 v164, s[98:99]
	s_add_u32 s100, s88, s16
	s_addc_u32 s101, s89, s17
	s_add_i32 m0, s75, s60
	s_andn2_b64 vcc, exec, s[0:1]
	global_load_lds_dwordx4 v164, s[100:101]
	s_cbranch_vccnz .LBB0_1026
	s_add_i32 s0, s72, 47
	s_cmp_le_u32 s0, s6
	s_cbranch_scc1 .LBB0_1025
	v_cmp_lt_i32_e32 vcc, -1, v170
	s_nop 1
	v_cndmask_b32_e32 v98, v167, v98, vcc
	v_cmp_lt_i32_e32 vcc, 31, v170
	s_nop 1
	v_cndmask_b32_e32 v82, v167, v82, vcc
	v_cmp_lt_i32_e32 vcc, 0, v170
	s_nop 1
	v_cndmask_b32_e32 v99, v167, v99, vcc
	v_cmp_lt_i32_e32 vcc, 32, v170
	s_nop 1
	v_cndmask_b32_e32 v83, v167, v83, vcc
	v_cmp_lt_i32_e32 vcc, 1, v170
	s_nop 1
	v_cndmask_b32_e32 v100, v167, v100, vcc
	v_cmp_lt_i32_e32 vcc, 33, v170
	s_nop 1
	v_cndmask_b32_e32 v84, v167, v84, vcc
	v_cmp_lt_i32_e32 vcc, 2, v170
	s_nop 1
	v_cndmask_b32_e32 v101, v167, v101, vcc
	v_cmp_lt_i32_e32 vcc, 34, v170
	s_nop 1
	v_cndmask_b32_e32 v85, v167, v85, vcc
	v_cmp_lt_i32_e32 vcc, 7, v170
	s_nop 1
	v_cndmask_b32_e32 v102, v167, v102, vcc
	v_cmp_lt_i32_e32 vcc, 39, v170
	s_nop 1
	v_cndmask_b32_e32 v86, v167, v86, vcc
	v_cmp_lt_i32_e32 vcc, 8, v170
	s_nop 1
	v_cndmask_b32_e32 v103, v167, v103, vcc
	v_cmp_lt_i32_e32 vcc, 40, v170
	s_nop 1
	v_cndmask_b32_e32 v87, v167, v87, vcc
	v_cmp_lt_i32_e32 vcc, 9, v170
	s_nop 1
	v_cndmask_b32_e32 v104, v167, v104, vcc
	v_cmp_lt_i32_e32 vcc, 41, v170
	s_nop 1
	v_cndmask_b32_e32 v88, v167, v88, vcc
	v_cmp_lt_i32_e32 vcc, 10, v170
	s_nop 1
	v_cndmask_b32_e32 v105, v167, v105, vcc
	v_cmp_lt_i32_e32 vcc, 42, v170
	s_nop 1
	v_cndmask_b32_e32 v89, v167, v89, vcc
	v_cmp_lt_i32_e32 vcc, 15, v170
	s_nop 1
	v_cndmask_b32_e32 v106, v167, v106, vcc
	v_cmp_lt_i32_e32 vcc, 47, v170
	s_nop 1
	v_cndmask_b32_e32 v90, v167, v90, vcc
	v_cmp_lt_i32_e32 vcc, 16, v170
	s_nop 1
	v_cndmask_b32_e32 v107, v167, v107, vcc
	v_cmp_lt_i32_e32 vcc, 48, v170
	s_nop 1
	v_cndmask_b32_e32 v91, v167, v91, vcc
	v_cmp_lt_i32_e32 vcc, 17, v170
	s_nop 1
	v_cndmask_b32_e32 v108, v167, v108, vcc
	v_cmp_lt_i32_e32 vcc, 49, v170
	s_nop 1
	v_cndmask_b32_e32 v92, v167, v92, vcc
	v_cmp_lt_i32_e32 vcc, 18, v170
	s_nop 1
	v_cndmask_b32_e32 v109, v167, v109, vcc
	v_cmp_lt_i32_e32 vcc, 50, v170
	s_nop 1
	v_cndmask_b32_e32 v93, v167, v93, vcc
	v_cmp_lt_i32_e32 vcc, 23, v170
	s_nop 1
	v_cndmask_b32_e32 v110, v167, v110, vcc
	v_cmp_lt_i32_e32 vcc, 55, v170
	s_nop 1
	v_cndmask_b32_e32 v94, v167, v94, vcc
	v_cmp_lt_i32_e32 vcc, 24, v170
	s_nop 1
	v_cndmask_b32_e32 v111, v167, v111, vcc
	v_cmp_lt_i32_e32 vcc, 56, v170
	s_nop 1
	v_cndmask_b32_e32 v95, v167, v95, vcc
	v_cmp_lt_i32_e32 vcc, 25, v170
	s_nop 1
	v_cndmask_b32_e32 v112, v167, v112, vcc
	v_cmp_lt_i32_e32 vcc, 57, v170
	s_nop 1
	v_cndmask_b32_e32 v96, v167, v96, vcc
	v_cmp_lt_i32_e32 vcc, 26, v170
	s_nop 1
	v_cndmask_b32_e32 v113, v167, v113, vcc
	v_cmp_lt_i32_e32 vcc, 58, v170
	s_nop 1
	v_cndmask_b32_e32 v97, v167, v97, vcc
	s_branch .LBB0_1025

; __global__ void __launch_bounds__(NWAVES * 64, 2) fwd_kernel(Args args) {
	.amdhsa_kernel _Z10fwd_kernel4Args
		.amdhsa_group_segment_fixed_size 0
		.amdhsa_private_segment_fixed_size 0
		.amdhsa_kernarg_size 456
		.amdhsa_user_sgpr_count 2
		.amdhsa_user_sgpr_dispatch_ptr 0
		.amdhsa_user_sgpr_queue_ptr 0
		.amdhsa_user_sgpr_kernarg_segment_ptr 1
		.amdhsa_user_sgpr_dispatch_id 0
		.amdhsa_user_sgpr_kernarg_preload_length 0
		.amdhsa_user_sgpr_kernarg_preload_offset 0
		.amdhsa_user_sgpr_private_segment_size 0
		.amdhsa_uses_dynamic_stack 0
		.amdhsa_enable_private_segment 0
		.amdhsa_system_sgpr_workgroup_id_x 1
		.amdhsa_system_sgpr_workgroup_id_y 0
		.amdhsa_system_sgpr_workgroup_id_z 0
		.amdhsa_system_sgpr_workgroup_info 0
		.amdhsa_system_vgpr_workitem_id 0
		.amdhsa_next_free_vgpr 255
		.amdhsa_next_free_sgpr 102
		.amdhsa_accum_offset 256
		.amdhsa_reserve_vcc 1
		.amdhsa_float_round_mode_32 0
		.amdhsa_float_round_mode_16_64 0
		.amdhsa_float_denorm_mode_32 3
		.amdhsa_float_denorm_mode_16_64 3
		.amdhsa_dx10_clamp 1
		.amdhsa_ieee_mode 1
		.amdhsa_fp16_overflow 0
		.amdhsa_tg_split 0
		.amdhsa_exception_fp_ieee_invalid_op 0
		.amdhsa_exception_fp_denorm_src 0
		.amdhsa_exception_fp_ieee_div_zero 0
		.amdhsa_exception_fp_ieee_overflow 0
		.amdhsa_exception_fp_ieee_underflow 0
		.amdhsa_exception_fp_ieee_inexact 0
		.amdhsa_exception_int_div_zero 0
	.end_amdhsa_kernel

; __global__ void __launch_bounds__(NWAVES * 64, 2) fwd_kernel(Args args) {
amdhsa.kernels:
  - .agpr_count:     0
    .args:
      - .offset:         0
        .size:           200
        .value_kind:     by_value
      - .offset:         200
        .size:           4
        .value_kind:     hidden_block_count_x
      - .offset:         204
        .size:           4
        .value_kind:     hidden_block_count_y
      - .offset:         208
        .size:           4
        .value_kind:     hidden_block_count_z
      - .offset:         212
        .size:           2
        .value_kind:     hidden_group_size_x
      - .offset:         214
        .size:           2
        .value_kind:     hidden_group_size_y
      - .offset:         216
        .size:           2
        .value_kind:     hidden_group_size_z
      - .offset:         218
        .size:           2
        .value_kind:     hidden_remainder_x
      - .offset:         220
        .size:           2
        .value_kind:     hidden_remainder_y
      - .offset:         222
        .size:           2
        .value_kind:     hidden_remainder_z
      - .offset:         240
        .size:           8
        .value_kind:     hidden_global_offset_x
      - .offset:         248
        .size:           8
        .value_kind:     hidden_global_offset_y
      - .offset:         256
        .size:           8
        .value_kind:     hidden_global_offset_z
      - .offset:         264
        .size:           2
        .value_kind:     hidden_grid_dims
      - .offset:         320
        .size:           4
        .value_kind:     hidden_dynamic_lds_size
    .group_segment_fixed_size: 0
    .kernarg_segment_align: 8
    .kernarg_segment_size: 456
    .language:       OpenCL C
    .language_version:
      - 2
      - 0
    .max_flat_workgroup_size: 512
    .name:           _Z10fwd_kernel4Args
    .private_segment_fixed_size: 0
    .sgpr_count:     108
    .sgpr_spill_count: 24
    .symbol:         _Z10fwd_kernel4Args.kd
    .uniform_work_group_size: 1
    .uses_dynamic_stack: false
    .vgpr_count:     255
    .vgpr_spill_count: 0
    .wavefront_size: 64
